# final norm phase: split-K residual passes of the sample rows software-pipelined two deep
# baseline (speedup 1.0000x reference)
; template <int MODE>
; __device__ __forceinline__ void norm_phase(const Params& p, int bid, int nblk) {
;     ...
;             const float* pb = (const float*)(p.ws + (MODE == 1 ? WS_PB10 : WS_PB13)) + (size_t)(row - TP) * DM;
;             const float* gt = mod + (size_t)bidx_of_row(row) * MODW + (MODE == 1 ? 4096 : 10240);
;             float* xo = p.out + O_Y + (size_t)row * DM;
;             constexpr int NPC = MODE == 1 ? 8 : 11;
; #pragma unroll 1
;             for (int i = 0; i < 8; ++i) { const int c = i * 256 + lane * 4; f32x4 s = *(const f32x4*)(pb + c);
; #pragma unroll
;                 for (int q = 1; q < NPC; ++q) s += *(const f32x4*)(pb + (size_t)q * TS * DM + c);
;                 const f32x4 base = MODE == 1 ? *(const f32x4*)(xs + c) : *(const f32x4*)(xo + c);
;                 *(f32x4*)(xo + c) = base + *(const f32x4*)(gt + c) * s; }
;             asm volatile("s_waitcnt vmcnt(0)" ::: "memory");
.LBB0_2026:
	s_cmpk_lt_i32 s12, 0x2000
	s_cbranch_scc1 .LBB0_2030
	s_add_i32 s2, s12, 0xffffe000
	s_lshl_b64 s[14:15], s[2:3], 13
	s_mov_b32 s13, s3
	s_lshr_b32 s2, s2, 2
	s_lshl_b64 s[26:27], s[12:13], 13
	v_lshl_add_u64 v[104:105], v[98:99], 0, s[14:15]
	v_mad_u64_u32 v[108:109], s[14:15], s2, v112, v[102:103]
	v_lshl_add_u64 v[106:107], v[100:101], 0, s[26:27]
	s_mov_b64 s[14:15], 0
	v_lshl_add_u64 v[158:159], v[104:105], 0, s[14:15]
	v_add_co_u32_e32 v118, vcc, 0x17ab9000, v158
	v_lshl_add_u64 v[166:167], v[106:107], 0, s[14:15]
	s_nop 0
	v_addc_co_u32_e32 v119, vcc, 0, v159, vcc
	v_add_co_u32_e32 v122, vcc, 0x17eb9000, v158
	global_load_dwordx4 v[114:117], v[166:167], off
	s_nop 0
	v_addc_co_u32_e32 v123, vcc, 0, v159, vcc
	v_add_co_u32_e32 v126, vcc, 0x182b9000, v158
	global_load_dwordx4 v[118:121], v[118:119], off
	s_nop 0
	global_load_dwordx4 v[122:125], v[122:123], off
	v_addc_co_u32_e32 v127, vcc, 0, v159, vcc
	v_add_co_u32_e32 v130, vcc, 0x186b9000, v158
	v_lshl_add_u64 v[162:163], v[108:109], 0, s[14:15]
	s_nop 0
	v_addc_co_u32_e32 v131, vcc, 0, v159, vcc
	v_add_co_u32_e32 v134, vcc, 0x18ab9000, v158
	global_load_dwordx4 v[126:129], v[126:127], off
	s_nop 0
	global_load_dwordx4 v[130:133], v[130:131], off
	v_addc_co_u32_e32 v135, vcc, 0, v159, vcc
	v_add_co_u32_e32 v138, vcc, 0x18eb9000, v158
	s_nop 0
	v_addc_co_u32_e32 v139, vcc, 0, v159, vcc
	v_add_co_u32_e32 v142, vcc, 0x192b9000, v158
	global_load_dwordx4 v[134:137], v[134:135], off
	s_nop 0
	global_load_dwordx4 v[138:141], v[138:139], off
	v_addc_co_u32_e32 v143, vcc, 0, v159, vcc
	v_add_co_u32_e32 v146, vcc, 0x196b9000, v158
	s_nop 0
	v_addc_co_u32_e32 v147, vcc, 0, v159, vcc
	v_add_co_u32_e32 v150, vcc, 0x19ab9000, v158
	global_load_dwordx4 v[142:145], v[142:143], off
	s_nop 0
	global_load_dwordx4 v[146:149], v[146:147], off
	v_addc_co_u32_e32 v151, vcc, 0, v159, vcc
	v_add_co_u32_e32 v154, vcc, 0x19eb9000, v158
	s_nop 0
	v_addc_co_u32_e32 v155, vcc, 0, v159, vcc
	v_add_co_u32_e32 v158, vcc, 0x1a2b9000, v158
	global_load_dwordx4 v[150:153], v[150:151], off
	s_nop 0
	global_load_dwordx4 v[154:157], v[154:155], off
	v_addc_co_u32_e32 v159, vcc, 0, v159, vcc
	global_load_dwordx4 v[158:161], v[158:159], off
	s_nop 0
	global_load_dwordx4 v[162:165], v[162:163], off
.LBB0_2028:
	s_add_u32 s34, s14, 0x400
	s_addc_u32 s35, s15, 0
	v_lshl_add_u64 v[214:215], v[104:105], 0, s[34:35]
	v_add_co_u32_e32 v172, vcc, 0x17ab9000, v214
	v_lshl_add_u64 v[222:223], v[106:107], 0, s[34:35]
	s_nop 0
	v_addc_co_u32_e32 v173, vcc, 0, v215, vcc
	v_add_co_u32_e32 v176, vcc, 0x17eb9000, v214
	global_load_dwordx4 v[168:171], v[222:223], off
	s_nop 0
	v_addc_co_u32_e32 v177, vcc, 0, v215, vcc
	v_add_co_u32_e32 v180, vcc, 0x182b9000, v214
	global_load_dwordx4 v[172:175], v[172:173], off
	s_nop 0
	global_load_dwordx4 v[176:179], v[176:177], off
	v_addc_co_u32_e32 v181, vcc, 0, v215, vcc
	v_add_co_u32_e32 v186, vcc, 0x186b9000, v214
	v_lshl_add_u64 v[218:219], v[108:109], 0, s[34:35]
	s_nop 0
	v_addc_co_u32_e32 v187, vcc, 0, v215, vcc
	v_add_co_u32_e32 v190, vcc, 0x18ab9000, v214
	global_load_dwordx4 v[180:183], v[180:181], off
	s_nop 0
	global_load_dwordx4 v[186:189], v[186:187], off
	v_addc_co_u32_e32 v191, vcc, 0, v215, vcc
	v_add_co_u32_e32 v194, vcc, 0x18eb9000, v214
	s_nop 0
	v_addc_co_u32_e32 v195, vcc, 0, v215, vcc
	v_add_co_u32_e32 v198, vcc, 0x192b9000, v214
	global_load_dwordx4 v[190:193], v[190:191], off
	s_nop 0
	global_load_dwordx4 v[194:197], v[194:195], off
	v_addc_co_u32_e32 v199, vcc, 0, v215, vcc
	v_add_co_u32_e32 v202, vcc, 0x196b9000, v214
	s_nop 0
	v_addc_co_u32_e32 v203, vcc, 0, v215, vcc
	v_add_co_u32_e32 v206, vcc, 0x19ab9000, v214
	global_load_dwordx4 v[198:201], v[198:199], off
	s_nop 0
	global_load_dwordx4 v[202:205], v[202:203], off
	v_addc_co_u32_e32 v207, vcc, 0, v215, vcc
	v_add_co_u32_e32 v210, vcc, 0x19eb9000, v214
	s_nop 0
	v_addc_co_u32_e32 v211, vcc, 0, v215, vcc
	v_add_co_u32_e32 v214, vcc, 0x1a2b9000, v214
	global_load_dwordx4 v[206:209], v[206:207], off
	s_nop 0
	global_load_dwordx4 v[210:213], v[210:211], off
	v_addc_co_u32_e32 v215, vcc, 0, v215, vcc
	global_load_dwordx4 v[214:217], v[214:215], off
	s_nop 0
	global_load_dwordx4 v[218:221], v[218:219], off
	s_cmp_lg_u32 s14, 0
	s_cbranch_scc1 .Lp14_w14
	s_waitcnt vmcnt(13)
	s_branch .Lp14_wd
.Lp14_w14:
	s_waitcnt vmcnt(14)
; template <int MODE>
; __device__ __forceinline__ void norm_phase(const Params& p, int bid, int nblk) {
;     ...
;             for (int i = 0; i < 8; ++i) { const int c = i * 256 + lane * 4; f32x4 s = *(const f32x4*)(pb + c);
; #pragma unroll
;                 for (int q = 1; q < NPC; ++q) s += *(const f32x4*)(pb + (size_t)q * TS * DM + c);
;                 const f32x4 base = MODE == 1 ? *(const f32x4*)(xs + c) : *(const f32x4*)(xo + c);
;                 *(f32x4*)(xo + c) = base + *(const f32x4*)(gt + c) * s; }
;             asm volatile("s_waitcnt vmcnt(0)" ::: "memory");
.Lp14_wd:
	v_pk_add_f32 v[120:121], v[120:121], v[124:125]
	v_pk_add_f32 v[118:119], v[118:119], v[122:123]
	v_pk_add_f32 v[120:121], v[120:121], v[128:129]
	v_pk_add_f32 v[118:119], v[118:119], v[126:127]
	v_pk_add_f32 v[120:121], v[120:121], v[132:133]
	v_pk_add_f32 v[118:119], v[118:119], v[130:131]
	v_pk_add_f32 v[120:121], v[120:121], v[136:137]
	v_pk_add_f32 v[118:119], v[118:119], v[134:135]
	v_pk_add_f32 v[120:121], v[120:121], v[140:141]
	v_pk_add_f32 v[118:119], v[118:119], v[138:139]
	v_pk_add_f32 v[120:121], v[120:121], v[144:145]
	v_pk_add_f32 v[118:119], v[118:119], v[142:143]
	v_pk_add_f32 v[120:121], v[120:121], v[148:149]
	v_pk_add_f32 v[118:119], v[118:119], v[146:147]
	v_pk_add_f32 v[120:121], v[120:121], v[152:153]
	v_pk_add_f32 v[118:119], v[118:119], v[150:151]
	v_pk_add_f32 v[120:121], v[120:121], v[156:157]
	v_pk_add_f32 v[118:119], v[118:119], v[154:155]
	v_pk_add_f32 v[120:121], v[120:121], v[160:161]
	v_pk_add_f32 v[118:119], v[118:119], v[158:159]
	v_pk_fma_f32 v[116:117], v[120:121], v[164:165], v[116:117]
	v_pk_fma_f32 v[114:115], v[118:119], v[162:163], v[114:115]
	global_store_dwordx4 v[166:167], v[114:117], off
	s_add_u32 s14, s14, 0x800
	s_addc_u32 s15, s15, 0
	s_cmpk_eq_i32 s14, 0x2000
	s_cbranch_scc1 .Lp14_last
	v_lshl_add_u64 v[158:159], v[104:105], 0, s[14:15]
	v_add_co_u32_e32 v118, vcc, 0x17ab9000, v158
	v_lshl_add_u64 v[166:167], v[106:107], 0, s[14:15]
	s_nop 0
	v_addc_co_u32_e32 v119, vcc, 0, v159, vcc
	v_add_co_u32_e32 v122, vcc, 0x17eb9000, v158
	global_load_dwordx4 v[114:117], v[166:167], off
	s_nop 0
	v_addc_co_u32_e32 v123, vcc, 0, v159, vcc
	v_add_co_u32_e32 v126, vcc, 0x182b9000, v158
	global_load_dwordx4 v[118:121], v[118:119], off
	s_nop 0
	global_load_dwordx4 v[122:125], v[122:123], off
	v_addc_co_u32_e32 v127, vcc, 0, v159, vcc
	v_add_co_u32_e32 v130, vcc, 0x186b9000, v158
	v_lshl_add_u64 v[162:163], v[108:109], 0, s[14:15]
	s_nop 0
	v_addc_co_u32_e32 v131, vcc, 0, v159, vcc
	v_add_co_u32_e32 v134, vcc, 0x18ab9000, v158
	global_load_dwordx4 v[126:129], v[126:127], off
	s_nop 0
	global_load_dwordx4 v[130:133], v[130:131], off
	v_addc_co_u32_e32 v135, vcc, 0, v159, vcc
	v_add_co_u32_e32 v138, vcc, 0x18eb9000, v158
	s_nop 0
	v_addc_co_u32_e32 v139, vcc, 0, v159, vcc
	v_add_co_u32_e32 v142, vcc, 0x192b9000, v158
	global_load_dwordx4 v[134:137], v[134:135], off
	s_nop 0
	global_load_dwordx4 v[138:141], v[138:139], off
	v_addc_co_u32_e32 v143, vcc, 0, v159, vcc
	v_add_co_u32_e32 v146, vcc, 0x196b9000, v158
	s_nop 0
	v_addc_co_u32_e32 v147, vcc, 0, v159, vcc
	v_add_co_u32_e32 v150, vcc, 0x19ab9000, v158
	global_load_dwordx4 v[142:145], v[142:143], off
	s_nop 0
	global_load_dwordx4 v[146:149], v[146:147], off
	v_addc_co_u32_e32 v151, vcc, 0, v159, vcc
	v_add_co_u32_e32 v154, vcc, 0x19eb9000, v158
	s_nop 0
	v_addc_co_u32_e32 v155, vcc, 0, v159, vcc
	v_add_co_u32_e32 v158, vcc, 0x1a2b9000, v158
	global_load_dwordx4 v[150:153], v[150:151], off
	s_nop 0
	global_load_dwordx4 v[154:157], v[154:155], off
	v_addc_co_u32_e32 v159, vcc, 0, v159, vcc
	global_load_dwordx4 v[158:161], v[158:159], off
	s_nop 0
	global_load_dwordx4 v[162:165], v[162:163], off
	s_waitcnt vmcnt(14)
	v_pk_add_f32 v[174:175], v[174:175], v[178:179]
	v_pk_add_f32 v[172:173], v[172:173], v[176:177]
	v_pk_add_f32 v[174:175], v[174:175], v[182:183]
	v_pk_add_f32 v[172:173], v[172:173], v[180:181]
	v_pk_add_f32 v[174:175], v[174:175], v[188:189]
	v_pk_add_f32 v[172:173], v[172:173], v[186:187]
	v_pk_add_f32 v[174:175], v[174:175], v[192:193]
	v_pk_add_f32 v[172:173], v[172:173], v[190:191]
	v_pk_add_f32 v[174:175], v[174:175], v[196:197]
	v_pk_add_f32 v[172:173], v[172:173], v[194:195]
	v_pk_add_f32 v[174:175], v[174:175], v[200:201]
	v_pk_add_f32 v[172:173], v[172:173], v[198:199]
	v_pk_add_f32 v[174:175], v[174:175], v[204:205]
	v_pk_add_f32 v[172:173], v[172:173], v[202:203]
	v_pk_add_f32 v[174:175], v[174:175], v[208:209]
	v_pk_add_f32 v[172:173], v[172:173], v[206:207]
	v_pk_add_f32 v[174:175], v[174:175], v[212:213]
	v_pk_add_f32 v[172:173], v[172:173], v[210:211]
	v_pk_add_f32 v[174:175], v[174:175], v[216:217]
	v_pk_add_f32 v[172:173], v[172:173], v[214:215]
	v_pk_fma_f32 v[170:171], v[174:175], v[220:221], v[170:171]
	v_pk_fma_f32 v[168:169], v[172:173], v[218:219], v[168:169]
	global_store_dwordx4 v[222:223], v[168:171], off
	s_branch .LBB0_2028
.Lp14_last:
	s_waitcnt vmcnt(1)
	v_pk_add_f32 v[174:175], v[174:175], v[178:179]
	v_pk_add_f32 v[172:173], v[172:173], v[176:177]
	v_pk_add_f32 v[174:175], v[174:175], v[182:183]
	v_pk_add_f32 v[172:173], v[172:173], v[180:181]
	v_pk_add_f32 v[174:175], v[174:175], v[188:189]
	v_pk_add_f32 v[172:173], v[172:173], v[186:187]
	v_pk_add_f32 v[174:175], v[174:175], v[192:193]
	v_pk_add_f32 v[172:173], v[172:173], v[190:191]
	v_pk_add_f32 v[174:175], v[174:175], v[196:197]
	v_pk_add_f32 v[172:173], v[172:173], v[194:195]
	v_pk_add_f32 v[174:175], v[174:175], v[200:201]
	v_pk_add_f32 v[172:173], v[172:173], v[198:199]
	v_pk_add_f32 v[174:175], v[174:175], v[204:205]
	v_pk_add_f32 v[172:173], v[172:173], v[202:203]
	v_pk_add_f32 v[174:175], v[174:175], v[208:209]
	v_pk_add_f32 v[172:173], v[172:173], v[206:207]
	v_pk_add_f32 v[174:175], v[174:175], v[212:213]
	v_pk_add_f32 v[172:173], v[172:173], v[210:211]
	v_pk_add_f32 v[174:175], v[174:175], v[216:217]
	v_pk_add_f32 v[172:173], v[172:173], v[214:215]
	v_pk_fma_f32 v[170:171], v[174:175], v[220:221], v[170:171]
	v_pk_fma_f32 v[168:169], v[172:173], v[218:219], v[168:169]
	global_store_dwordx4 v[222:223], v[168:171], off
	s_waitcnt vmcnt(0)
